# P0 x-row loop: row sum-of-squares butterfly by DPP / permlane swaps instead of 24 ds_bpermute round trips per iteration, stacked on v85
# speedup vs baseline: 1.0019x; 1.0019x over previous
.LBB0_107:
	s_add_i32 s2, s26, 0xffffc000
	s_ashr_i32 s27, s26, 31
	s_cmpk_lt_i32 s26, 0x4000
	v_readlane_b32 s72, v254, 10
	s_cselect_b32 s5, s27, 0
	s_cselect_b32 s4, s26, s2
	v_readlane_b32 s73, v254, 11
	v_readlane_b32 s74, v254, 12
	v_readlane_b32 s75, v254, 13
	s_cselect_b32 s2, s73, s75
	s_cselect_b32 s8, s72, s74
	s_lshl_b64 s[4:5], s[4:5], 12
	s_add_u32 s4, s8, s4
	s_addc_u32 s5, s2, s5
	global_load_dwordx4 v[68:71], v62, s[4:5] nt
	global_load_dwordx4 v[72:75], v62, s[4:5] offset:1024 nt
	global_load_dwordx4 v[76:79], v62, s[4:5] offset:2048 nt
	global_load_dwordx4 v[80:83], v62, s[4:5] offset:3072 nt
	s_add_i32 s30, s57, s26
	s_cmpk_lt_i32 s30, 0x4400
	s_cselect_b32 s2, s30, s26
	s_ashr_i32 s4, s2, 31
	s_add_i32 s8, s2, 0xffffc000
	s_cmpk_lt_i32 s2, 0x4000
	s_cselect_b32 s5, s4, 0
	s_cselect_b32 s4, s2, s8
	s_cselect_b32 s2, s73, s75
	s_cselect_b32 s8, s72, s74
	s_lshl_b64 s[4:5], s[4:5], 12
	s_add_u32 s4, s8, s4
	s_addc_u32 s5, s2, s5
	s_add_i32 s28, s36, s26
	s_cmpk_lt_i32 s28, 0x4400
	s_cselect_b32 s2, s28, s26
	global_load_dwordx4 v[50:53], v62, s[4:5] nt
	global_load_dwordx4 v[46:49], v62, s[4:5] offset:1024 nt
	global_load_dwordx4 v[38:41], v62, s[4:5] offset:2048 nt
	global_load_dwordx4 v[34:37], v62, s[4:5] offset:3072 nt
	s_ashr_i32 s4, s2, 31
	s_add_i32 s8, s2, 0xffffc000
	s_cmpk_lt_i32 s2, 0x4000
	s_cselect_b32 s5, s4, 0
	s_cselect_b32 s4, s2, s8
	s_cselect_b32 s2, s73, s75
	s_cselect_b32 s8, s72, s74
	s_lshl_b64 s[4:5], s[4:5], 12
	s_add_u32 s34, s8, s4
	s_addc_u32 s35, s2, s5
	s_mul_i32 s2, s54, 24
	s_add_i32 s4, s2, s26
	s_cmpk_lt_i32 s4, 0x4400
	s_cselect_b32 s2, s4, s26
	s_ashr_i32 s5, s2, 31
	s_add_i32 s8, s2, 0xffffc000
	s_cmpk_lt_i32 s2, 0x4000
	global_load_dwordx4 v[42:45], v62, s[34:35] nt
	global_load_dwordx4 v[30:33], v62, s[34:35] offset:1024 nt
	global_load_dwordx4 v[26:29], v62, s[34:35] offset:2048 nt
	global_load_dwordx4 v[22:25], v62, s[34:35] offset:3072 nt
	s_cselect_b32 s35, s5, 0
	s_cselect_b32 s34, s2, s8
	s_cselect_b32 s2, s73, s75
	s_cselect_b32 s5, s72, s74
	s_lshl_b64 s[34:35], s[34:35], 12
	s_add_u32 s34, s5, s34
	s_addc_u32 s35, s2, s35
	global_load_dwordx4 v[18:21], v62, s[34:35] nt
	global_load_dwordx4 v[14:17], v62, s[34:35] offset:1024 nt
	global_load_dwordx4 v[10:13], v62, s[34:35] offset:2048 nt
	global_load_dwordx4 v[6:9], v62, s[34:35] offset:3072 nt
	s_lshl_b64 s[34:35], s[26:27], 11
	v_readlane_b32 s76, v254, 14
	v_readlane_b32 s77, v254, 15
	v_readlane_b32 s78, v254, 16
	v_readlane_b32 s79, v254, 17
	v_readlane_b32 s80, v254, 18
	v_readlane_b32 s81, v254, 19
	v_readlane_b32 s82, v254, 20
	v_readlane_b32 s83, v254, 21
	v_readlane_b32 s84, v254, 22
	v_readlane_b32 s85, v254, 23
	v_readlane_b32 s86, v254, 24
	v_readlane_b32 s87, v254, 25
	s_waitcnt vmcnt(15)
	v_mul_f32_e32 v2, v69, v69
	s_waitcnt lgkmcnt(0)
	v_mul_f32_e32 v4, v71, v71
	s_waitcnt vmcnt(14)
	v_mul_f32_e32 v5, v73, v73
	v_mul_f32_e32 v63, v75, v75
	s_waitcnt vmcnt(13)
	v_mul_f32_e32 v64, v77, v77
	v_mul_f32_e32 v65, v79, v79
	v_fmac_f32_e32 v2, v68, v68
	v_fmac_f32_e32 v4, v70, v70
	v_fmac_f32_e32 v5, v72, v72
	v_fmac_f32_e32 v63, v74, v74
	s_waitcnt vmcnt(12)
	v_mul_f32_e32 v88, v81, v81
	v_mul_f32_e32 v89, v83, v83
	v_fmac_f32_e32 v64, v76, v76
	v_fmac_f32_e32 v65, v78, v78
	v_add_f32_e32 v2, v2, v4
	v_add_f32_e32 v4, v5, v63
	v_fmac_f32_e32 v88, v80, v80
	v_fmac_f32_e32 v89, v82, v82
	v_add_f32_e32 v5, v64, v65
	v_add_f32_e32 v2, v2, v4
	v_add_f32_e32 v63, v88, v89
	v_add_f32_e32 v2, v2, v5
	v_add_f32_e32 v2, v2, v63
	s_nop 1
	v_mov_b32_dpp v4, v2 quad_perm:[1,0,3,2] row_mask:0xf bank_mask:0xf
	v_lshl_add_u64 v[64:65], v[54:55], 0, s[34:35]
	s_waitcnt lgkmcnt(0)
	v_add_f32_e32 v2, v2, v4
	s_nop 1
	v_mov_b32_dpp v4, v2 quad_perm:[2,3,0,1] row_mask:0xf bank_mask:0xf
	s_waitcnt lgkmcnt(0)
	v_add_f32_e32 v2, v2, v4
	s_nop 1
	v_mov_b32_dpp v4, v2 row_half_mirror row_mask:0xf bank_mask:0xf
	s_waitcnt lgkmcnt(0)
	v_add_f32_e32 v2, v2, v4
	s_nop 1
	v_mov_b32_dpp v63, v2 row_mirror row_mask:0xf bank_mask:0xf
	v_cvt_pk_bf16_f32 v4, v68, v69
	v_cvt_pk_bf16_f32 v5, v70, v71
	global_store_dwordx2 v[64:65], v[4:5], off
	v_cvt_pk_bf16_f32 v4, v72, v73
	s_waitcnt lgkmcnt(0)
	v_add_f32_e32 v2, v2, v63
	v_mov_b32_e32 v63, v2
	s_nop 1
	v_permlane16_swap_b32_e32 v2, v63
	v_cvt_pk_bf16_f32 v5, v74, v75
	global_store_dwordx2 v[64:65], v[4:5], off offset:512
	v_cvt_pk_bf16_f32 v68, v76, v77
	v_cvt_pk_bf16_f32 v69, v78, v79
	s_waitcnt lgkmcnt(0)
	v_add_f32_e32 v2, v2, v63
	v_mov_b32_e32 v4, v2
	s_nop 1
	v_permlane32_swap_b32_e32 v2, v4
	global_store_dwordx2 v[64:65], v[68:69], off offset:1024
	v_cvt_pk_bf16_f32 v68, v80, v81
	v_cvt_pk_bf16_f32 v69, v82, v83
	global_store_dwordx2 v[64:65], v[68:69], off offset:1536
	s_and_saveexec_b64 s[34:35], vcc
	s_cbranch_execz .LBB0_109
	s_lshl_b64 s[38:39], s[26:27], 4
	s_add_u32 s38, s60, s38
	s_waitcnt lgkmcnt(0)
	v_add_f32_e32 v2, v2, v4
	s_addc_u32 s39, s61, s39
	v_mov_b32_e32 v4, v3
	v_mov_b32_e32 v5, v3
	global_store_dwordx4 v3, v[2:5], s[38:39]
.LBB0_109:
	s_or_b64 exec, exec, s[34:35]
	s_cmpk_gt_i32 s30, 0x43ff
	s_cbranch_scc1 .LBB0_106
	s_waitcnt vmcnt(15)
	v_mul_f32_e32 v2, v51, v51
	s_waitcnt lgkmcnt(0)
	v_mul_f32_e32 v4, v53, v53
	v_fmac_f32_e32 v2, v50, v50
	v_fmac_f32_e32 v4, v52, v52
	v_add_f32_e32 v2, v2, v4
	s_waitcnt vmcnt(14)
	v_mul_f32_e32 v4, v47, v47
	v_mul_f32_e32 v5, v49, v49
	v_fmac_f32_e32 v4, v46, v46
	v_fmac_f32_e32 v5, v48, v48
	v_add_f32_e32 v4, v4, v5
	v_add_f32_e32 v2, v2, v4
	s_waitcnt vmcnt(13)
	v_mul_f32_e32 v4, v39, v39
	v_mul_f32_e32 v5, v41, v41
	v_fmac_f32_e32 v4, v38, v38
	v_fmac_f32_e32 v5, v40, v40
	v_add_f32_e32 v4, v4, v5
	v_add_f32_e32 v2, v2, v4
	s_waitcnt vmcnt(12)
	v_mul_f32_e32 v4, v35, v35
	v_mul_f32_e32 v5, v37, v37
	v_fmac_f32_e32 v4, v34, v34
	v_fmac_f32_e32 v5, v36, v36
	v_add_f32_e32 v4, v4, v5
	v_add_f32_e32 v2, v2, v4
	s_nop 1
	v_mov_b32_dpp v4, v2 quad_perm:[1,0,3,2] row_mask:0xf bank_mask:0xf
	s_ashr_i32 s31, s30, 31
	s_lshl_b64 s[34:35], s[30:31], 11
	v_cvt_pk_bf16_f32 v50, v50, v51
	v_cvt_pk_bf16_f32 v51, v52, v53
	s_waitcnt lgkmcnt(0)
	v_add_f32_e32 v2, v2, v4
	s_nop 1
	v_mov_b32_dpp v4, v2 quad_perm:[2,3,0,1] row_mask:0xf bank_mask:0xf
	v_lshl_add_u64 v[52:53], v[54:55], 0, s[34:35]
	global_store_dwordx2 v[52:53], v[50:51], off
	v_cvt_pk_bf16_f32 v46, v46, v47
	v_cvt_pk_bf16_f32 v47, v48, v49
	s_waitcnt lgkmcnt(0)
	v_add_f32_e32 v2, v2, v4
	s_nop 1
	v_mov_b32_dpp v4, v2 row_half_mirror row_mask:0xf bank_mask:0xf
	global_store_dwordx2 v[52:53], v[46:47], off offset:512
	v_cvt_pk_bf16_f32 v38, v38, v39
	v_cvt_pk_bf16_f32 v39, v40, v41
	global_store_dwordx2 v[52:53], v[38:39], off offset:1024
	s_waitcnt lgkmcnt(0)
	v_add_f32_e32 v2, v2, v4
	s_nop 1
	v_mov_b32_dpp v4, v2 row_mirror row_mask:0xf bank_mask:0xf
	v_cvt_pk_bf16_f32 v34, v34, v35
	v_cvt_pk_bf16_f32 v35, v36, v37
	global_store_dwordx2 v[52:53], v[34:35], off offset:1536
	s_waitcnt lgkmcnt(0)
	v_add_f32_e32 v2, v2, v4
	v_mov_b32_e32 v4, v2
	s_nop 1
	v_permlane16_swap_b32_e32 v2, v4
	s_waitcnt lgkmcnt(0)
	v_add_f32_e32 v2, v2, v4
	v_mov_b32_e32 v4, v2
	s_nop 1
	v_permlane32_swap_b32_e32 v2, v4
	s_and_saveexec_b64 s[34:35], vcc
	s_cbranch_execz .LBB0_112
	s_lshl_b64 s[30:31], s[30:31], 4
	s_add_u32 s30, s60, s30
	s_waitcnt lgkmcnt(0)
	v_add_f32_e32 v2, v2, v4
	s_addc_u32 s31, s61, s31
	v_mov_b32_e32 v4, v3
	v_mov_b32_e32 v5, v3
	global_store_dwordx4 v3, v[2:5], s[30:31]
.LBB0_112:
	s_or_b64 exec, exec, s[34:35]
	s_cmpk_gt_i32 s28, 0x43ff
	s_cbranch_scc1 .LBB0_106
	s_waitcnt vmcnt(15)
	v_mul_f32_e32 v2, v43, v43
	s_waitcnt lgkmcnt(0)
	v_mul_f32_e32 v4, v45, v45
	v_fmac_f32_e32 v2, v42, v42
	v_fmac_f32_e32 v4, v44, v44
	v_add_f32_e32 v2, v2, v4
	s_waitcnt vmcnt(14)
	v_mul_f32_e32 v4, v31, v31
	v_mul_f32_e32 v5, v33, v33
	v_fmac_f32_e32 v4, v30, v30
	v_fmac_f32_e32 v5, v32, v32
	v_add_f32_e32 v4, v4, v5
	v_add_f32_e32 v2, v2, v4
	s_waitcnt vmcnt(13)
	v_mul_f32_e32 v4, v27, v27
	v_mul_f32_e32 v5, v29, v29
	v_fmac_f32_e32 v4, v26, v26
	v_fmac_f32_e32 v5, v28, v28
	v_add_f32_e32 v4, v4, v5
	v_add_f32_e32 v2, v2, v4
	s_waitcnt vmcnt(12)
	v_mul_f32_e32 v4, v23, v23
	v_mul_f32_e32 v5, v25, v25
	v_fmac_f32_e32 v4, v22, v22
	v_fmac_f32_e32 v5, v24, v24
	v_add_f32_e32 v4, v4, v5
	v_add_f32_e32 v2, v2, v4
	s_nop 1
	v_mov_b32_dpp v4, v2 quad_perm:[1,0,3,2] row_mask:0xf bank_mask:0xf
	s_ashr_i32 s29, s28, 31
	s_lshl_b64 s[30:31], s[28:29], 11
	v_lshl_add_u64 v[36:37], v[54:55], 0, s[30:31]
	v_cvt_pk_bf16_f32 v34, v42, v43
	s_waitcnt lgkmcnt(0)
	v_add_f32_e32 v2, v2, v4
	s_nop 1
	v_mov_b32_dpp v4, v2 quad_perm:[2,3,0,1] row_mask:0xf bank_mask:0xf
	v_cvt_pk_bf16_f32 v35, v44, v45
	global_store_dwordx2 v[36:37], v[34:35], off
	v_cvt_pk_bf16_f32 v30, v30, v31
	v_cvt_pk_bf16_f32 v31, v32, v33
	s_waitcnt lgkmcnt(0)
	v_add_f32_e32 v2, v2, v4
	s_nop 1
	v_mov_b32_dpp v4, v2 row_half_mirror row_mask:0xf bank_mask:0xf
	global_store_dwordx2 v[36:37], v[30:31], off offset:512
	v_cvt_pk_bf16_f32 v26, v26, v27
	v_cvt_pk_bf16_f32 v27, v28, v29
	global_store_dwordx2 v[36:37], v[26:27], off offset:1024
	s_waitcnt lgkmcnt(0)
	v_add_f32_e32 v2, v2, v4
	s_nop 1
	v_mov_b32_dpp v4, v2 row_mirror row_mask:0xf bank_mask:0xf
	v_cvt_pk_bf16_f32 v22, v22, v23
	v_cvt_pk_bf16_f32 v23, v24, v25
	global_store_dwordx2 v[36:37], v[22:23], off offset:1536
	s_waitcnt lgkmcnt(0)
	v_add_f32_e32 v2, v2, v4
	v_mov_b32_e32 v4, v2
	s_nop 1
	v_permlane16_swap_b32_e32 v2, v4
	s_waitcnt lgkmcnt(0)
	v_add_f32_e32 v2, v2, v4
	v_mov_b32_e32 v4, v2
	s_nop 1
	v_permlane32_swap_b32_e32 v2, v4
	s_and_saveexec_b64 s[30:31], vcc
	s_cbranch_execz .LBB0_115
	s_lshl_b64 s[28:29], s[28:29], 4
	s_add_u32 s28, s60, s28
	s_waitcnt lgkmcnt(0)
	v_add_f32_e32 v2, v2, v4
	s_addc_u32 s29, s61, s29
	v_mov_b32_e32 v4, v3
	v_mov_b32_e32 v5, v3
	global_store_dwordx4 v3, v[2:5], s[28:29]
.LBB0_115:
	s_or_b64 exec, exec, s[30:31]
	s_cmpk_gt_i32 s4, 0x43ff
	s_cbranch_scc1 .LBB0_106
	s_waitcnt vmcnt(15)
	v_mul_f32_e32 v2, v19, v19
	s_waitcnt lgkmcnt(0)
	v_mul_f32_e32 v4, v21, v21
	v_fmac_f32_e32 v2, v18, v18
	v_fmac_f32_e32 v4, v20, v20
	v_add_f32_e32 v2, v2, v4
	s_waitcnt vmcnt(14)
	v_mul_f32_e32 v4, v15, v15
	v_mul_f32_e32 v5, v17, v17
	v_fmac_f32_e32 v4, v14, v14
	v_fmac_f32_e32 v5, v16, v16
	v_add_f32_e32 v4, v4, v5
	v_add_f32_e32 v2, v2, v4
	s_waitcnt vmcnt(13)
	v_mul_f32_e32 v4, v11, v11
	v_mul_f32_e32 v5, v13, v13
	v_fmac_f32_e32 v4, v10, v10
	v_fmac_f32_e32 v5, v12, v12
	v_add_f32_e32 v4, v4, v5
	v_add_f32_e32 v2, v2, v4
	s_waitcnt vmcnt(12)
	v_mul_f32_e32 v4, v7, v7
	v_mul_f32_e32 v5, v9, v9
	v_fmac_f32_e32 v4, v6, v6
	v_fmac_f32_e32 v5, v8, v8
	v_add_f32_e32 v4, v4, v5
	v_add_f32_e32 v2, v2, v4
	s_nop 1
	v_mov_b32_dpp v4, v2 quad_perm:[1,0,3,2] row_mask:0xf bank_mask:0xf
	s_ashr_i32 s5, s4, 31
	s_lshl_b64 s[28:29], s[4:5], 11
	v_cvt_pk_bf16_f32 v18, v18, v19
	v_cvt_pk_bf16_f32 v19, v20, v21
	s_waitcnt lgkmcnt(0)
	v_add_f32_e32 v2, v2, v4
	s_nop 1
	v_mov_b32_dpp v4, v2 quad_perm:[2,3,0,1] row_mask:0xf bank_mask:0xf
	v_lshl_add_u64 v[20:21], v[54:55], 0, s[28:29]
	global_store_dwordx2 v[20:21], v[18:19], off
	v_cvt_pk_bf16_f32 v14, v14, v15
	v_cvt_pk_bf16_f32 v15, v16, v17
	s_waitcnt lgkmcnt(0)
	v_add_f32_e32 v2, v2, v4
	s_nop 1
	v_mov_b32_dpp v4, v2 row_half_mirror row_mask:0xf bank_mask:0xf
	global_store_dwordx2 v[20:21], v[14:15], off offset:512
	v_cvt_pk_bf16_f32 v10, v10, v11
	v_cvt_pk_bf16_f32 v11, v12, v13
	global_store_dwordx2 v[20:21], v[10:11], off offset:1024
	s_waitcnt lgkmcnt(0)
	v_add_f32_e32 v2, v2, v4
	s_nop 1
	v_mov_b32_dpp v4, v2 row_mirror row_mask:0xf bank_mask:0xf
	v_cvt_pk_bf16_f32 v6, v6, v7
	v_cvt_pk_bf16_f32 v7, v8, v9
	global_store_dwordx2 v[20:21], v[6:7], off offset:1536
	s_waitcnt lgkmcnt(0)
	v_add_f32_e32 v2, v2, v4
	v_mov_b32_e32 v4, v2
	s_nop 1
	v_permlane16_swap_b32_e32 v2, v4
	s_waitcnt lgkmcnt(0)
	v_add_f32_e32 v2, v2, v4
	v_mov_b32_e32 v4, v2
	s_nop 1
	v_permlane32_swap_b32_e32 v2, v4
	s_and_saveexec_b64 s[28:29], vcc
	s_cbranch_execz .LBB0_105
	s_lshl_b64 s[4:5], s[4:5], 4
	s_add_u32 s4, s60, s4
	s_waitcnt lgkmcnt(0)
	v_add_f32_e32 v2, v2, v4
	s_addc_u32 s5, s61, s5
	v_mov_b32_e32 v4, v3
	v_mov_b32_e32 v5, v3
	global_store_dwordx4 v3, v[2:5], s[4:5]
	s_branch .LBB0_105
